# FoX attention main loop: K-fragment LDS reads software-pipelined by one MFMA in both QK^T sections
# speedup vs baseline: 1.0036x; 1.0014x over previous
; __device__ __forceinline__ void finishSM(f32x16& p0, f32x16& p1, float alpha, float& l_reg, bf16x8& pa0, bf16x8& pa1, bf16x8& pa2, bf16x8& pa3) {
;     for (int r = 0; r < 16; ++r) p1[r] = __builtin_amdgcn_exp2f(p1[r]);
;     float ps = 0; for (int r = 0; r < 16; ++r) ps += p0[r]; for (int r = 0; r < 16; ++r) ps += p1[r];
;     { auto rr = __builtin_amdgcn_permlane32_swap(__float_as_uint(ps), __float_as_uint(ps), false, false);
;       ps = __uint_as_float(rr[0]) + __uint_as_float(rr[1]); }
;     l_reg = l_reg * alpha + ps;
;     ...
;     PK4(p0, 0, pa0); PK4(p0, 8, pa1); PK4(p1, 0, pa2); PK4(p1, 8, pa3);
; template <int KB, bool SK>
; __device__ __forceinline__ void qkt(f32x16& p0, f32x16& p1, const char* K_lds, int r32, int hi, const bf16x8* qr, bool act, int cbo  ) {
;     if (SK && !act) { const float NEG = -__builtin_inff();
; #pragma unroll
;         for (int r = 0; r < 16; ++r) { p0[r] = NEG; p1[r] = NEG; } return; }
;     if (cbo >= 0) { int a_ = cbo + hi * 16; asm volatile("" : "+v"(a_)); const __attribute__((address_space(3))) float* cb = (const __attribute__((address_space(3))) float*)(unsigned)a_;
; #pragma unroll
;         for (int q_ = 0; q_ < 4; ++q_) { const f32x4 v0_ = *(const __attribute__((address_space(3))) f32x4*)(cb + 8 * q_), v1_ = *(const __attribute__((address_space(3))) f32x4*)(cb + 32 + 8 * q_);
; #pragma unroll
;             for (int j_ = 0; j_ < 4; ++j_) { p0[4 * q_ + j_] = v0_[j_]; p1[4 * q_ + j_] = v1_[j_]; } }
;     } else { p0 = f32x16{}; p1 = f32x16{}; }
;     const char* kb[4];
; #pragma unroll
;     for (int dd = 0; dd < 4; ++dd) kb[dd] = K_lds + KB * SHM_K + KSWZ(r32, (dd * 16 + hi * 8) * 2);
; #pragma unroll
;     for (int d0 = 0; d0 < 8; ++d0) { const char* a = kb[d0 & 3] + (d0 >> 2) * 128;
;         bf16x8 b0 = *reinterpret_cast<const bf16x8*>(a);
;         bf16x8 b1 = *reinterpret_cast<const bf16x8*>(a + 32 * 256);
;         p0 = __builtin_amdgcn_mfma_f32_32x32x16_bf16(b0, qr[d0], p0, 0, 0, 0);
;         p1 = __builtin_amdgcn_mfma_f32_32x32x16_bf16(b1, qr[d0], p1, 0, 0, 0); }
.LBB0_893:
	v_add_u32_e32 v2, 0xffffff00, v221
	v_add_u32_e32 v227, v15, v217
	ds_read_b128 v[100:103], v2
	ds_read_b128 v[104:107], v2 offset:32
	ds_read_b128 v[84:87], v2 offset:128
	ds_read_b128 v[88:91], v2 offset:160
	ds_read_b128 v[108:111], v2 offset:64
	ds_read_b128 v[92:95], v2 offset:192
	s_waitcnt vmcnt(0)
	ds_read_b128 v[112:115], v2 offset:96
	ds_read_b128 v[96:99], v2 offset:224
	ds_read_b128 v[2:5], v227 offset:49152
	ds_read_b128 v[6:9], v227 offset:57344
	v_add_u32_e32 v195, v15, v218
	s_waitcnt lgkmcnt(1)
	v_mfma_f32_32x32x16_bf16 v[100:115], v[2:5], v[172:175], v[100:115]
	ds_read_b128 v[2:5], v195 offset:49152
	v_add_u32_e32 v194, v15, v219
	v_add_u32_e32 v193, v15, v220
	v_add_f32_e32 v80, 0, v190
	v_add_f32_e32 v80, v192, v80
	v_add_f32_e32 v80, v188, v80
	v_add_f32_e32 v80, v191, v80
	v_add_f32_e32 v80, v186, v80
	s_waitcnt lgkmcnt(1)
	v_mfma_f32_32x32x16_bf16 v[84:99], v[6:9], v[172:175], v[84:99]
	ds_read_b128 v[6:9], v195 offset:57344
	v_add_f32_e32 v80, v189, v80
	v_add_f32_e32 v80, v185, v80
	v_add_f32_e32 v80, v187, v80
	v_add_f32_e32 v80, v178, v80
	v_add_f32_e32 v80, v182, v80
	v_add_f32_e32 v80, v177, v80
	s_waitcnt lgkmcnt(1)
	v_mfma_f32_32x32x16_bf16 v[100:115], v[2:5], v[168:171], v[100:115]
	ds_read_b128 v[2:5], v194 offset:49152
	v_add_f32_e32 v80, v179, v80
	v_add_f32_e32 v80, v176, v80
	v_add_f32_e32 v80, v184, v80
	v_add_f32_e32 v80, v181, v80
	v_add_f32_e32 v80, v183, v80
	v_exp_f32_e32 v10, v134
	v_exp_f32_e32 v11, v135
	s_waitcnt lgkmcnt(1)
	v_mfma_f32_32x32x16_bf16 v[84:99], v[6:9], v[168:171], v[84:99]
	ds_read_b128 v[6:9], v194 offset:57344
	v_exp_f32_e32 v12, v132
	v_exp_f32_e32 v13, v133
	v_exp_f32_e32 v126, v130
	v_exp_f32_e32 v127, v131
	v_exp_f32_e32 v128, v128
	v_exp_f32_e32 v129, v129
	s_waitcnt lgkmcnt(1)
	v_mfma_f32_32x32x16_bf16 v[100:115], v[2:5], v[164:167], v[100:115]
	ds_read_b128 v[2:5], v193 offset:49152
	s_add_i32 s12, s56, 0xffffff81
	s_sub_i32 s13, s56, 64
	s_waitcnt lgkmcnt(1)
	v_mfma_f32_32x32x16_bf16 v[84:99], v[6:9], v[164:167], v[84:99]
	ds_read_b128 v[6:9], v193 offset:57344
	s_waitcnt lgkmcnt(1)
	v_mfma_f32_32x32x16_bf16 v[100:115], v[2:5], v[160:163], v[100:115]
	ds_read_b128 v[2:5], v227 offset:49280
	s_waitcnt lgkmcnt(1)
	v_mfma_f32_32x32x16_bf16 v[84:99], v[6:9], v[160:163], v[84:99]
	ds_read_b128 v[6:9], v227 offset:57472
	s_waitcnt lgkmcnt(1)
	v_mfma_f32_32x32x16_bf16 v[100:115], v[2:5], v[156:159], v[100:115]
	ds_read_b128 v[2:5], v195 offset:49280
	s_waitcnt lgkmcnt(1)
	v_mfma_f32_32x32x16_bf16 v[84:99], v[6:9], v[156:159], v[84:99]
	ds_read_b128 v[6:9], v195 offset:57472
	s_waitcnt lgkmcnt(1)
	v_mfma_f32_32x32x16_bf16 v[100:115], v[2:5], v[152:155], v[100:115]
	ds_read_b128 v[2:5], v194 offset:49280
	s_waitcnt lgkmcnt(1)
	v_mfma_f32_32x32x16_bf16 v[84:99], v[6:9], v[152:155], v[84:99]
	ds_read_b128 v[6:9], v194 offset:57472
	s_waitcnt lgkmcnt(1)
	v_mfma_f32_32x32x16_bf16 v[100:115], v[2:5], v[148:151], v[100:115]
	ds_read_b128 v[2:5], v193 offset:49280
	s_waitcnt lgkmcnt(1)
	v_mfma_f32_32x32x16_bf16 v[84:99], v[6:9], v[148:151], v[84:99]
	ds_read_b128 v[6:9], v193 offset:57472
	s_waitcnt lgkmcnt(1)
	v_mfma_f32_32x32x16_bf16 v[100:115], v[2:5], v[144:147], v[100:115]
	v_exp_f32_e32 v2, v142
	v_exp_f32_e32 v3, v143
	v_exp_f32_e32 v4, v140
	v_exp_f32_e32 v5, v141
	v_add_f32_e32 v80, v2, v80
	v_add_f32_e32 v80, v3, v80
	v_add_f32_e32 v80, v4, v80
	s_waitcnt lgkmcnt(0)
	v_mfma_f32_32x32x16_bf16 v[84:99], v[6:9], v[144:147], v[84:99]
	v_exp_f32_e32 v6, v138
	v_exp_f32_e32 v7, v139
	v_exp_f32_e32 v8, v136
	v_exp_f32_e32 v9, v137
	v_add_f32_e32 v80, v5, v80
	v_add_f32_e32 v80, v6, v80
	v_add_f32_e32 v80, v7, v80
	v_add_f32_e32 v80, v8, v80
	v_add_f32_e32 v80, v9, v80
	v_add_f32_e32 v80, v10, v80
	v_add_f32_e32 v80, v11, v80
	v_add_f32_e32 v80, v12, v80
	v_add_f32_e32 v80, v13, v80
	v_add_f32_e32 v80, v126, v80
	v_add_f32_e32 v80, v127, v80
	v_add_f32_e32 v80, v128, v80
	v_add_f32_e32 v223, v129, v80
	v_mov_b32_e32 v224, v223
	s_nop 1
	v_permlane32_swap_b32_e32 v223, v224
	v_cvt_pk_bf16_f32 v80, v190, v192
	v_cvt_pk_bf16_f32 v81, v188, v191
	v_cvt_pk_bf16_f32 v82, v186, v189
	v_cvt_pk_bf16_f32 v83, v185, v187
	v_cvt_pk_bf16_f32 v116, v178, v182
	v_cvt_pk_bf16_f32 v117, v177, v179
	v_cvt_pk_bf16_f32 v118, v176, v184
	v_cvt_pk_bf16_f32 v119, v181, v183
	v_cvt_pk_bf16_f32 v120, v2, v3
	v_cvt_pk_bf16_f32 v121, v4, v5
	v_cvt_pk_bf16_f32 v122, v6, v7
	v_cvt_pk_bf16_f32 v123, v8, v9
	v_cvt_pk_bf16_f32 v124, v10, v11
	v_cvt_pk_bf16_f32 v125, v12, v13
	v_cvt_pk_bf16_f32 v126, v126, v127
	v_cvt_pk_bf16_f32 v127, v128, v129
	s_nop 0
	v_permlane32_swap_b32_e32 v80, v82
	v_permlane32_swap_b32_e32 v81, v83
	v_permlane32_swap_b32_e32 v116, v118
	v_permlane32_swap_b32_e32 v117, v119
	v_permlane32_swap_b32_e32 v120, v122
	v_permlane32_swap_b32_e32 v121, v123
	v_permlane32_swap_b32_e32 v124, v126
	v_permlane32_swap_b32_e32 v125, v127
	v_add_u32_e32 v10, 0x2000, v0
	v_mov_b32_e32 v11, v1
	v_lshl_add_u64 v[2:3], s[50:51], 0, v[0:1]
	v_lshl_add_u64 v[6:7], s[50:51], 0, v[10:11]
	v_lshl_add_u64 v[12:13], s[14:15], 0, v[0:1]
	flat_load_dwordx4 v[2:5], v[2:3]
	s_nop 0
	flat_load_dwordx4 v[6:9], v[6:7]
	v_lshl_add_u64 v[128:129], s[14:15], 0, v[10:11]
	flat_load_dwordx4 v[10:13], v[12:13]
	s_nop 0
	flat_load_dwordx4 v[176:179], v[128:129]
	ds_read_b64_tr_b16 v[128:129], v204 offset:0
	ds_read_b64_tr_b16 v[130:131], v204 offset:0x800
	ds_read_b64_tr_b16 v[132:133], v204 offset:0x1000
	ds_read_b64_tr_b16 v[134:135], v204 offset:0x1800
	ds_read_b64_tr_b16 v[136:137], v204 offset:0x2000
	ds_read_b64_tr_b16 v[138:139], v204 offset:0x2800
	ds_read_b64_tr_b16 v[140:141], v204 offset:0x3000
	ds_read_b64_tr_b16 v[142:143], v204 offset:0x3800
	s_waitcnt lgkmcnt(0)
; __device__ __forceinline__ void mask_tile(f32x16& p0, f32x16& p1, int dq, unsigned W) {
;     const float NEG = -__builtin_inff();
; #pragma unroll
;     for (int r = 0; r < 16; ++r) {
;         const int c = (r & 3) + 8 * (r >> 2);
;         if ((unsigned)(dq - c) >= W) p0[r] = NEG;
;         if ((unsigned)(dq - c - 32) >= W) p1[r] = NEG;
;     }
; }
; template <int VB, bool SK>
; __device__ __forceinline__ void pv_tile(f32x16* o, int vb0, bf16x8 pa0, bf16x8 pa1, bf16x8 pa2, bf16x8 pa3, bool act) {
;     ...
;     PV_D0(0); PV_D0(1); PV_D0(2); PV_D0(3);
	s_nop 0
	v_mfma_f32_32x32x16_bf16 v[64:79], v[80:83], v[128:131], v[64:79]
	ds_read_b64_tr_b16 v[128:129], v204 offset:0x200
	ds_read_b64_tr_b16 v[130:131], v204 offset:0xa00
	v_mfma_f32_32x32x16_bf16 v[64:79], v[116:119], v[132:135], v[64:79]
	ds_read_b64_tr_b16 v[132:133], v204 offset:0x1200
	ds_read_b64_tr_b16 v[134:135], v204 offset:0x1a00
	v_mfma_f32_32x32x16_bf16 v[64:79], v[120:123], v[136:139], v[64:79]
	ds_read_b64_tr_b16 v[136:137], v204 offset:0x2200
	ds_read_b64_tr_b16 v[138:139], v204 offset:0x2a00
	v_mfma_f32_32x32x16_bf16 v[64:79], v[124:127], v[140:143], v[64:79]
	ds_read_b64_tr_b16 v[140:141], v204 offset:0x3200
	ds_read_b64_tr_b16 v[142:143], v204 offset:0x3a00
	s_waitcnt lgkmcnt(0)
	v_mfma_f32_32x32x16_bf16 v[48:63], v[80:83], v[128:131], v[48:63]
	ds_read_b64_tr_b16 v[128:129], v204 offset:0x400
	ds_read_b64_tr_b16 v[130:131], v204 offset:0xc00
	v_mfma_f32_32x32x16_bf16 v[48:63], v[116:119], v[132:135], v[48:63]
	ds_read_b64_tr_b16 v[132:133], v204 offset:0x1400
	ds_read_b64_tr_b16 v[134:135], v204 offset:0x1c00
	v_mfma_f32_32x32x16_bf16 v[48:63], v[120:123], v[136:139], v[48:63]
	ds_read_b64_tr_b16 v[136:137], v204 offset:0x2400
	ds_read_b64_tr_b16 v[138:139], v204 offset:0x2c00
	v_mfma_f32_32x32x16_bf16 v[48:63], v[124:127], v[140:143], v[48:63]
	ds_read_b64_tr_b16 v[140:141], v204 offset:0x3400
	ds_read_b64_tr_b16 v[142:143], v204 offset:0x3c00
	s_waitcnt lgkmcnt(0)
	v_mfma_f32_32x32x16_bf16 v[32:47], v[80:83], v[128:131], v[32:47]
	ds_read_b64_tr_b16 v[128:129], v204 offset:0x600
	ds_read_b64_tr_b16 v[130:131], v204 offset:0xe00
	v_mfma_f32_32x32x16_bf16 v[32:47], v[116:119], v[132:135], v[32:47]
	ds_read_b64_tr_b16 v[132:133], v204 offset:0x1600
	ds_read_b64_tr_b16 v[134:135], v204 offset:0x1e00
	v_mfma_f32_32x32x16_bf16 v[32:47], v[120:123], v[136:139], v[32:47]
	ds_read_b64_tr_b16 v[136:137], v204 offset:0x2600
	ds_read_b64_tr_b16 v[138:139], v204 offset:0x2e00
	v_mfma_f32_32x32x16_bf16 v[32:47], v[124:127], v[140:143], v[32:47]
	ds_read_b64_tr_b16 v[140:141], v204 offset:0x3600
	ds_read_b64_tr_b16 v[142:143], v204 offset:0x3e00
	s_waitcnt lgkmcnt(0)
	v_mfma_f32_32x32x16_bf16 v[16:31], v[80:83], v[128:131], v[16:31]
	s_cmp_le_i32 s13, s18
	s_cselect_b64 s[36:37], -1, 0
	s_cmp_gt_i32 s12, s19
	s_cselect_b64 s[12:13], -1, 0
	s_and_b64 s[12:13], s[36:37], s[12:13]
	s_and_b64 vcc, exec, s[12:13]
	v_mfma_f32_32x32x16_bf16 v[16:31], v[116:119], v[132:135], v[16:31]
	v_mfma_f32_32x32x16_bf16 v[16:31], v[120:123], v[136:139], v[16:31]
	v_mfma_f32_32x32x16_bf16 v[16:31], v[124:127], v[140:143], v[16:31]
	s_cbranch_vccnz .LBB0_895
	v_add_u32_e32 v80, 0x10007b, v222
	v_cmp_gt_u32_e32 vcc, s39, v80
	v_add_u32_e32 v80, 0x5b, v222
	s_nop 0
	v_cndmask_b32_e32 v100, v196, v100, vcc
	v_cmp_lt_u32_e32 vcc, s42, v80
	v_add_u32_e32 v80, 0x7a, v222
	s_nop 0
	v_cndmask_b32_e32 v84, v196, v84, vcc
	v_cmp_lt_u32_e32 vcc, s42, v80
	v_add_u32_e32 v80, 0x5a, v222
	s_nop 0
	v_cndmask_b32_e32 v101, v196, v101, vcc
	v_cmp_lt_u32_e32 vcc, s42, v80
	v_add_u32_e32 v80, 0x79, v222
	s_nop 0
	v_cndmask_b32_e32 v85, v196, v85, vcc
	v_cmp_lt_u32_e32 vcc, s42, v80
	v_add_u32_e32 v80, 0x59, v222
	s_nop 0
	v_cndmask_b32_e32 v102, v196, v102, vcc
	v_cmp_lt_u32_e32 vcc, s42, v80
	v_add_u32_e32 v80, 0x78, v222
	s_nop 0
	v_cndmask_b32_e32 v86, v196, v86, vcc
	v_cmp_lt_u32_e32 vcc, s42, v80
	v_add_u32_e32 v80, 0x58, v222
	s_nop 0
	v_cndmask_b32_e32 v103, v196, v103, vcc
	v_cmp_lt_u32_e32 vcc, s42, v80
	v_add_u32_e32 v80, 0x73, v222
	s_nop 0
	v_cndmask_b32_e32 v87, v196, v87, vcc
	v_cmp_lt_u32_e32 vcc, s42, v80
	v_add_u32_e32 v80, 0x53, v222
	s_nop 0
	v_cndmask_b32_e32 v104, v196, v104, vcc
	v_cmp_lt_u32_e32 vcc, s42, v80
	v_add_u32_e32 v80, 0x72, v222
	s_nop 0
	v_cndmask_b32_e32 v88, v196, v88, vcc
	v_cmp_lt_u32_e32 vcc, s42, v80
	v_add_u32_e32 v80, 0x52, v222
	s_nop 0
	v_cndmask_b32_e32 v105, v196, v105, vcc
	v_cmp_lt_u32_e32 vcc, s42, v80
	v_add_u32_e32 v80, 0x71, v222
	s_nop 0
	v_cndmask_b32_e32 v89, v196, v89, vcc
	v_cmp_lt_u32_e32 vcc, s42, v80
	v_add_u32_e32 v80, 0x51, v222
	s_nop 0
	v_cndmask_b32_e32 v106, v196, v106, vcc
	v_cmp_lt_u32_e32 vcc, s42, v80
	v_add_u32_e32 v80, 0x70, v222
	s_nop 0
	v_cndmask_b32_e32 v90, v196, v90, vcc
	v_cmp_lt_u32_e32 vcc, s42, v80
	v_add_u32_e32 v80, 0x50, v222
	s_nop 0
	v_cndmask_b32_e32 v107, v196, v107, vcc
	v_cmp_lt_u32_e32 vcc, s42, v80
	v_add_u32_e32 v80, 0x6b, v222
	s_nop 0
	v_cndmask_b32_e32 v91, v196, v91, vcc
	v_cmp_lt_u32_e32 vcc, s42, v80
	v_add_u32_e32 v80, 0x4b, v222
	s_nop 0
	v_cndmask_b32_e32 v108, v196, v108, vcc
	v_cmp_lt_u32_e32 vcc, s42, v80
	v_add_u32_e32 v80, 0x6a, v222
	s_nop 0
	v_cndmask_b32_e32 v92, v196, v92, vcc
	v_cmp_lt_u32_e32 vcc, s42, v80
	v_add_u32_e32 v80, 0x4a, v222
	s_nop 0
	v_cndmask_b32_e32 v109, v196, v109, vcc
	v_cmp_lt_u32_e32 vcc, s42, v80
	v_add_u32_e32 v80, 0x69, v222
	s_nop 0
	v_cndmask_b32_e32 v93, v196, v93, vcc
	v_cmp_lt_u32_e32 vcc, s42, v80
	v_add_u32_e32 v80, 0x49, v222
	s_nop 0
	v_cndmask_b32_e32 v110, v196, v110, vcc
	v_cmp_lt_u32_e32 vcc, s42, v80
	v_add_u32_e32 v80, 0x68, v222
	s_nop 0
	v_cndmask_b32_e32 v94, v196, v94, vcc
	v_cmp_lt_u32_e32 vcc, s42, v80
	v_add_u32_e32 v80, 0x48, v222
	s_nop 0
	v_cndmask_b32_e32 v111, v196, v111, vcc
	v_cmp_lt_u32_e32 vcc, s42, v80
	v_add_u32_e32 v80, 0x63, v222
	s_nop 0
	v_cndmask_b32_e32 v95, v196, v95, vcc
	v_cmp_lt_u32_e32 vcc, s42, v80
	v_add_u32_e32 v80, 0x43, v222
	s_nop 0
	v_cndmask_b32_e32 v112, v196, v112, vcc
	v_cmp_lt_u32_e32 vcc, s42, v80
	v_add_u32_e32 v80, 0x62, v222
	s_nop 0
	v_cndmask_b32_e32 v96, v196, v96, vcc
	v_cmp_lt_u32_e32 vcc, s42, v80
	v_add_u32_e32 v80, 0x42, v222
	s_nop 0
	v_cndmask_b32_e32 v113, v196, v113, vcc
	v_cmp_lt_u32_e32 vcc, s42, v80
	v_add_u32_e32 v80, 0x61, v222
	s_nop 0
	v_cndmask_b32_e32 v97, v196, v97, vcc
	v_cmp_lt_u32_e32 vcc, s42, v80
	v_add_u32_e32 v80, 0x41, v222
	s_nop 0
	v_cndmask_b32_e32 v114, v196, v114, vcc
	v_cmp_lt_u32_e32 vcc, s42, v80
	v_add_u32_e32 v80, 0x60, v222
	s_nop 0
	v_cndmask_b32_e32 v98, v196, v98, vcc
	v_cmp_lt_u32_e32 vcc, s42, v80
	v_add_u32_e32 v80, 64, v222
	s_nop 0
	v_cndmask_b32_e32 v115, v196, v115, vcc
	v_cmp_lt_u32_e32 vcc, s42, v80
	s_nop 1
	v_cndmask_b32_e32 v99, v196, v99, vcc

; __device__ __forceinline__ void partialSM(f32x16& p0, f32x16& p1, float& m_reg, float& mn, float& alpha) {
;     ...
;     constexpr float C2 = 1.4426950408889634f * SCALE;
;     if (__builtin_expect(__all((pmax - m_reg) * SCALE <= THR), 1)) { mn = m_reg; alpha = 1.f; }
;     else { mn = fmaxf(m_reg, pmax); alpha = __builtin_amdgcn_exp2f((m_reg - mn) * C2); m_reg = mn; }
;     const float mnL = -mn * C2;
;     for (int r = 0; r < 16; ++r) p0[r] = fmaf(p0[r], C2, mnL); for (int r = 0; r < 16; ++r) p1[r] = fmaf(p1[r], C2, mnL);
;     for (int r = 0; r < 16; ++r) p0[r] = __builtin_amdgcn_exp2f(p0[r]);
.LBB0_899:
	v_cndmask_b32_e64 v226, v80, v180, s[36:37]
	v_mul_f32_e32 v180, 0xbe0293ee, v226
	v_fmamk_f32 v80, v100, 0x3e0293ee, v180
	v_fmamk_f32 v81, v101, 0x3e0293ee, v180
	v_fmamk_f32 v82, v102, 0x3e0293ee, v180
	v_fmamk_f32 v83, v103, 0x3e0293ee, v180
	v_fmamk_f32 v116, v104, 0x3e0293ee, v180
	v_fmamk_f32 v117, v105, 0x3e0293ee, v180
	v_fmamk_f32 v118, v106, 0x3e0293ee, v180
	v_fmamk_f32 v119, v107, 0x3e0293ee, v180
	v_fmamk_f32 v120, v108, 0x3e0293ee, v180
	v_fmamk_f32 v121, v109, 0x3e0293ee, v180
	v_fmamk_f32 v122, v110, 0x3e0293ee, v180
	v_fmamk_f32 v123, v111, 0x3e0293ee, v180
	v_fmamk_f32 v112, v112, 0x3e0293ee, v180
	v_fmamk_f32 v113, v113, 0x3e0293ee, v180
	v_fmamk_f32 v114, v114, 0x3e0293ee, v180
	v_fmamk_f32 v115, v115, 0x3e0293ee, v180
	v_fmamk_f32 v100, v84, 0x3e0293ee, v180
	v_fmamk_f32 v109, v85, 0x3e0293ee, v180
	v_fmamk_f32 v110, v86, 0x3e0293ee, v180
	v_fmamk_f32 v111, v87, 0x3e0293ee, v180
	v_fmamk_f32 v181, v88, 0x3e0293ee, v180
	v_fmamk_f32 v101, v89, 0x3e0293ee, v180
	v_fmamk_f32 v102, v90, 0x3e0293ee, v180
	v_fmamk_f32 v103, v91, 0x3e0293ee, v180
	v_fmamk_f32 v104, v92, 0x3e0293ee, v180
	v_fmamk_f32 v105, v93, 0x3e0293ee, v180
	v_fmamk_f32 v106, v94, 0x3e0293ee, v180
	v_fmamk_f32 v107, v95, 0x3e0293ee, v180
	v_exp_f32_e32 v80, v80
	v_exp_f32_e32 v81, v81
	v_exp_f32_e32 v82, v82
	v_exp_f32_e32 v83, v83
	v_exp_f32_e32 v84, v116
	v_exp_f32_e32 v85, v117
	v_exp_f32_e32 v86, v118
	v_exp_f32_e32 v87, v119
	v_exp_f32_e32 v88, v120
	v_exp_f32_e32 v89, v121
	v_exp_f32_e32 v90, v122
	v_exp_f32_e32 v91, v123
	v_exp_f32_e32 v92, v112
	v_exp_f32_e32 v93, v113
	v_exp_f32_e32 v94, v114
	v_exp_f32_e32 v95, v115
	v_fmamk_f32 v108, v96, 0x3e0293ee, v180
	v_fmamk_f32 v182, v97, 0x3e0293ee, v180
	v_fmamk_f32 v183, v98, 0x3e0293ee, v180
	v_fmac_f32_e32 v180, 0x3e0293ee, v99
	s_waitcnt lgkmcnt(0)
	s_barrier
; __device__ __forceinline__ void finishSM(f32x16& p0, f32x16& p1, float alpha, float& l_reg, bf16x8& pa0, bf16x8& pa1, bf16x8& pa2, bf16x8& pa3) {
;     for (int r = 0; r < 16; ++r) p1[r] = __builtin_amdgcn_exp2f(p1[r]);
;     float ps = 0; for (int r = 0; r < 16; ++r) ps += p0[r]; for (int r = 0; r < 16; ++r) ps += p1[r];
;     { auto rr = __builtin_amdgcn_permlane32_swap(__float_as_uint(ps), __float_as_uint(ps), false, false);
;       ps = __uint_as_float(rr[0]) + __uint_as_float(rr[1]); }
;     l_reg = l_reg * alpha + ps;
;     ...
;     PK4(p0, 0, pa0); PK4(p0, 8, pa1); PK4(p1, 0, pa2); PK4(p1, 8, pa3);
; template <int KB, bool SK>
; __device__ __forceinline__ void qkt(f32x16& p0, f32x16& p1, const char* K_lds, int r32, int hi, const bf16x8* qr, bool act, int cbo  ) {
;     if (SK && !act) { const float NEG = -__builtin_inff();
; #pragma unroll
;         for (int r = 0; r < 16; ++r) { p0[r] = NEG; p1[r] = NEG; } return; }
;     if (cbo >= 0) { int a_ = cbo + hi * 16; asm volatile("" : "+v"(a_)); const __attribute__((address_space(3))) float* cb = (const __attribute__((address_space(3))) float*)(unsigned)a_;
; #pragma unroll
;         for (int q_ = 0; q_ < 4; ++q_) { const f32x4 v0_ = *(const __attribute__((address_space(3))) f32x4*)(cb + 8 * q_), v1_ = *(const __attribute__((address_space(3))) f32x4*)(cb + 32 + 8 * q_);
; #pragma unroll
;             for (int j_ = 0; j_ < 4; ++j_) { p0[4 * q_ + j_] = v0_[j_]; p1[4 * q_ + j_] = v1_[j_]; } }
;     } else { p0 = f32x16{}; p1 = f32x16{}; }
;     const char* kb[4];
; #pragma unroll
;     for (int dd = 0; dd < 4; ++dd) kb[dd] = K_lds + KB * SHM_K + KSWZ(r32, (dd * 16 + hi * 8) * 2);
; #pragma unroll
;     for (int d0 = 0; d0 < 8; ++d0) { const char* a = kb[d0 & 3] + (d0 >> 2) * 128;
;         bf16x8 b0 = *reinterpret_cast<const bf16x8*>(a);
;         bf16x8 b1 = *reinterpret_cast<const bf16x8*>(a + 32 * 256);
;         p0 = __builtin_amdgcn_mfma_f32_32x32x16_bf16(b0, qr[d0], p0, 0, 0, 0);
;         p1 = __builtin_amdgcn_mfma_f32_32x32x16_bf16(b1, qr[d0], p1, 0, 0, 0); }
	v_mov_b32_e32 v96, v221
	ds_read_b128 v[128:131], v96
	ds_read_b128 v[132:135], v96 offset:32
	ds_read_b128 v[112:115], v96 offset:128
	ds_read_b128 v[116:119], v96 offset:160
	ds_read_b128 v[136:139], v96 offset:64
	ds_read_b128 v[120:123], v96 offset:192
	ds_read_b128 v[140:143], v96 offset:96
	ds_read_b128 v[124:127], v96 offset:224
	ds_read_b128 v[96:99], v227 offset:32768
	ds_read_b128 v[184:187], v227 offset:40960
	v_exp_f32_e32 v101, v101
	v_exp_f32_e32 v102, v102
	v_exp_f32_e32 v103, v103
	s_waitcnt lgkmcnt(1)
	v_mfma_f32_32x32x16_bf16 v[128:143], v[96:99], v[172:175], v[128:143]
	ds_read_b128 v[96:99], v195 offset:32768
	v_exp_f32_e32 v104, v104
	v_exp_f32_e32 v105, v105
	v_exp_f32_e32 v106, v106
	v_exp_f32_e32 v107, v107
	v_exp_f32_e32 v108, v108
	s_waitcnt lgkmcnt(1)
	v_mfma_f32_32x32x16_bf16 v[112:127], v[184:187], v[172:175], v[112:127]
	ds_read_b128 v[184:187], v195 offset:40960
	s_waitcnt lgkmcnt(1)
	v_mfma_f32_32x32x16_bf16 v[128:143], v[96:99], v[168:171], v[128:143]
	ds_read_b128 v[96:99], v194 offset:32768
	s_waitcnt lgkmcnt(1)
	v_mfma_f32_32x32x16_bf16 v[112:127], v[184:187], v[168:171], v[112:127]
	ds_read_b128 v[184:187], v194 offset:40960
	s_waitcnt lgkmcnt(1)
	v_mfma_f32_32x32x16_bf16 v[128:143], v[96:99], v[164:167], v[128:143]
	ds_read_b128 v[96:99], v193 offset:32768
	s_waitcnt lgkmcnt(1)
	v_mfma_f32_32x32x16_bf16 v[112:127], v[184:187], v[164:167], v[112:127]
	ds_read_b128 v[184:187], v193 offset:40960
	s_waitcnt lgkmcnt(1)
	v_mfma_f32_32x32x16_bf16 v[128:143], v[96:99], v[160:163], v[128:143]
	ds_read_b128 v[96:99], v227 offset:32896
	s_waitcnt lgkmcnt(1)
	v_mfma_f32_32x32x16_bf16 v[112:127], v[184:187], v[160:163], v[112:127]
	ds_read_b128 v[184:187], v227 offset:41088
	s_waitcnt lgkmcnt(1)
	v_mfma_f32_32x32x16_bf16 v[128:143], v[96:99], v[156:159], v[128:143]
	ds_read_b128 v[96:99], v195 offset:32896
	s_waitcnt lgkmcnt(1)
	v_mfma_f32_32x32x16_bf16 v[112:127], v[184:187], v[156:159], v[112:127]
	ds_read_b128 v[184:187], v195 offset:41088
	s_waitcnt lgkmcnt(1)
	v_mfma_f32_32x32x16_bf16 v[128:143], v[96:99], v[152:155], v[128:143]
	ds_read_b128 v[96:99], v194 offset:32896
	s_waitcnt lgkmcnt(1)
	v_mfma_f32_32x32x16_bf16 v[112:127], v[184:187], v[152:155], v[112:127]
	ds_read_b128 v[184:187], v194 offset:41088
	s_waitcnt lgkmcnt(1)
	v_mfma_f32_32x32x16_bf16 v[128:143], v[96:99], v[148:151], v[128:143]
	ds_read_b128 v[96:99], v193 offset:32896
	s_waitcnt lgkmcnt(1)
	v_mfma_f32_32x32x16_bf16 v[112:127], v[184:187], v[148:151], v[112:127]
	ds_read_b128 v[184:187], v193 offset:41088
	s_waitcnt lgkmcnt(1)
	v_mfma_f32_32x32x16_bf16 v[128:143], v[96:99], v[144:147], v[128:143]
	v_exp_f32_e32 v99, v111
	v_exp_f32_e32 v111, v180
	v_add_f32_e32 v180, 0, v80
	v_add_f32_e32 v180, v81, v180
	v_add_f32_e32 v180, v82, v180
	v_add_f32_e32 v180, v83, v180
	v_add_f32_e32 v180, v84, v180
	v_add_f32_e32 v180, v85, v180
	v_add_f32_e32 v180, v86, v180
	v_add_f32_e32 v180, v87, v180
	v_add_f32_e32 v180, v88, v180
	v_add_f32_e32 v180, v89, v180
	v_add_f32_e32 v180, v90, v180
	v_add_f32_e32 v180, v91, v180
	v_exp_f32_e32 v96, v100
	v_add_f32_e32 v180, v92, v180
	v_exp_f32_e32 v97, v109
	v_add_f32_e32 v180, v93, v180
	v_exp_f32_e32 v98, v110
	v_add_f32_e32 v180, v94, v180
	v_add_f32_e32 v180, v95, v180
	v_exp_f32_e32 v100, v181
	v_add_f32_e32 v180, v96, v180
	v_add_f32_e32 v180, v97, v180
	v_add_f32_e32 v180, v98, v180
	v_add_f32_e32 v180, v99, v180
	v_add_f32_e32 v180, v100, v180
	v_add_f32_e32 v180, v101, v180
	v_add_f32_e32 v180, v102, v180
	v_add_f32_e32 v180, v103, v180
	v_add_f32_e32 v180, v104, v180
	v_exp_f32_e32 v109, v182
	v_add_f32_e32 v180, v105, v180
	s_waitcnt lgkmcnt(0)
	v_mfma_f32_32x32x16_bf16 v[112:127], v[184:187], v[144:147], v[112:127]
	v_exp_f32_e32 v110, v183
	v_add_f32_e32 v180, v106, v180
	v_add_f32_e32 v180, v107, v180
	v_add_f32_e32 v180, v108, v180
	v_add_f32_e32 v180, v109, v180
	v_add_f32_e32 v180, v110, v180
	v_add_f32_e32 v227, v111, v180
	v_mov_b32_e32 v228, v227
	v_cvt_pk_bf16_f32 v180, v80, v81
	v_cvt_pk_bf16_f32 v181, v82, v83
	v_cvt_pk_bf16_f32 v182, v84, v85
	v_cvt_pk_bf16_f32 v183, v86, v87
	v_cvt_pk_bf16_f32 v184, v88, v89
	v_cvt_pk_bf16_f32 v185, v90, v91
	v_cvt_pk_bf16_f32 v186, v92, v93
	v_cvt_pk_bf16_f32 v187, v94, v95
	v_cvt_pk_bf16_f32 v188, v96, v97
	v_cvt_pk_bf16_f32 v189, v98, v99
	v_cvt_pk_bf16_f32 v190, v100, v101
	v_cvt_pk_bf16_f32 v191, v102, v103
	v_cvt_pk_bf16_f32 v192, v104, v105
	v_cvt_pk_bf16_f32 v193, v106, v107
	v_cvt_pk_bf16_f32 v194, v108, v109
	v_cvt_pk_bf16_f32 v195, v110, v111
	s_nop 1
	v_permlane32_swap_b32_e32 v227, v228
	v_permlane32_swap_b32_e32 v180, v182
	v_permlane32_swap_b32_e32 v181, v183
	v_permlane32_swap_b32_e32 v184, v186
	v_permlane32_swap_b32_e32 v185, v187
	v_permlane32_swap_b32_e32 v188, v190
	v_permlane32_swap_b32_e32 v189, v191
	v_permlane32_swap_b32_e32 v192, v194
	v_permlane32_swap_b32_e32 v193, v195
	s_add_i32 s36, s47, 1
	s_cmp_lt_i32 s36, s46
	s_cselect_b64 s[12:13], -1, 0
	s_cmp_ge_i32 s36, s46
	s_cbranch_scc1 .LBB0_901
	v_add_u32_e32 v10, 0x4000, v0
	v_mov_b32_e32 v11, v1
	v_add_u32_e32 v12, 0x6000, v0
	v_mov_b32_e32 v13, v1
	v_lshl_add_u64 v[2:3], s[50:51], 0, v[10:11]
	v_lshl_add_u64 v[6:7], s[50:51], 0, v[12:13]
	v_lshl_add_u64 v[10:11], s[14:15], 0, v[10:11]
	v_lshl_add_u64 v[176:177], s[14:15], 0, v[12:13]
	flat_load_dwordx4 v[2:5], v[2:3]
	s_nop 0
	flat_load_dwordx4 v[6:9], v[6:7]
	s_nop 0
	flat_load_dwordx4 v[10:13], v[10:11]
	s_nop 0
	flat_load_dwordx4 v[176:179], v[176:177]
